# GDN prep: 64x64 triangular solve moved to f32 matrix cores (blocked 16x16, v_mfma_f32_16x16x4_f32), LDS-transposed 16-byte stores
# speedup vs baseline: 1.0284x; 1.0108x over previous
; DEVI float bf2f(bf16_t b) { return __uint_as_float(((unsigned)b) << 16); }
; DEVI void prep_item(const Params& p, int j, int n, int h, char* smem) {
;     ...
;   {
;     bf16_t* kt = r0 + R0_KT + (size_t)(n * 8 + h) * 8192;
; #pragma unroll
;     for (int i = 0; i < 4; ++i) {
;       const int unit = tid + i * 256, d = unit >> 3, i0 = (unit & 7) * 8;
;       unsigned e[8];
; #pragma unroll
;       for (int q = 0; q < 8; ++q) e[q] = *(const unsigned short*)(ks + (i0 + q) * 272 + d * 2);
;       u32x4 o = {e[0] | (e[1] << 16), e[2] | (e[3] << 16), e[4] | (e[5] << 16), e[6] | (e[7] << 16)};
;       *(u32x4*)(kt + d * 64 + i0) = o;
;     }
;   }
;   {
;     const int c = tid;
;     const bool isu = c < 128;
;     const char* src = isu ? (vs + c * 2) : (ks + (c - 128) * 2);
;     float x[64];
; #pragma unroll
;     for (int i = 0; i < 64; ++i) x[i] = 0.f;
;     int zero;
;     asm volatile("v_mov_b32 %0, 0" : "=v"(zero));
; #pragma unroll
;     for (int i = 0; i < 64; ++i) {
;       const float* amz = am + zero;
;       const float* sbz = sbeta + zero;
;       const float eg = __expf(sbz[64 + i]);
;       float acc = bf2f(*(const unsigned short*)(src + i * 272)) * sbz[i] * (isu ? 1.0f : eg);
; #pragma unroll
;       for (int j4 = 0; j4 < (i + 3) / 4; ++j4) {
;         const f32x4 a = *(const f32x4*)(amz + i * 68 + j4 * 4);
;         acc -= a[0] * x[j4 * 4 + 0];
;         acc -= a[1] * x[j4 * 4 + 1];
;         acc -= a[2] * x[j4 * 4 + 2];
;         acc -= a[3] * x[j4 * 4 + 3];
;       }
;       asm volatile("" : "+v"(zero), "+v"(acc));
;       x[i] = acc;
;     }
.LBB0_1293:
	s_or_b64 exec, exec, s[0:1]
	v_mul_f32_e32 v2, v5, v2
	v_cvt_pk_bf16_f32 v2, v2, s0
	v_cmp_le_i32_e32 vcc, v0, v53
	v_and_b32_e32 v4, 56, v41
	v_ashrrev_i32_e32 v8, 3, v34
	v_cndmask_b32_e32 v0, 0, v2, vcc
	global_store_short v[20:21], v0, off offset:72
	v_lshlrev_b32_e32 v0, 5, v4
	v_and_b32_e32 v85, 24, v4
	v_and_b32_e32 v10, 32, v4
	v_lshrrev_b32_e32 v85, 1, v85
	v_or_b32_e32 v10, v10, v85
	v_mul_u32_u24_e32 v10, 0x110, v10
	v_lshlrev_b32_e32 v4, 1, v8
	v_add3_u32 v4, 32, v4, v10
	ds_write_b32 v45, v3 offset:53232
	s_waitcnt lgkmcnt(0)
	s_barrier
	v_lshlrev_b64 v[2:3], 14, v[36:37]
	ds_read_u16 v5, v4 offset:17408
	ds_read_u16 v9, v4 offset:17680
	ds_read_u16 v11, v4 offset:17952
	ds_read_u16 v12, v4 offset:18224
	ds_read_u16 v13, v4 offset:21760
	ds_read_u16 v14, v4 offset:22032
	ds_read_u16 v15, v4 offset:22304
	ds_read_u16 v16, v4 offset:22576
	v_lshl_add_u64 v[2:3], s[30:31], 0, v[2:3]
	v_lshl_add_u64 v[6:7], v[2:3], 0, v[0:1]
	v_ashrrev_i32_e32 v0, 3, v40
	s_waitcnt lgkmcnt(4)
	v_lshl_or_b32 v3, v12, 16, v11
	v_lshlrev_b32_e32 v11, 1, v0
	v_add3_u32 v11, 32, v11, v10
	v_lshl_or_b32 v2, v9, 16, v5
	s_waitcnt lgkmcnt(2)
	v_lshl_or_b32 v4, v14, 16, v13
	s_waitcnt lgkmcnt(0)
	v_lshl_or_b32 v5, v16, 16, v15
	ds_read_u16 v12, v11 offset:17408
	ds_read_u16 v13, v11 offset:17680
	ds_read_u16 v14, v11 offset:17952
	ds_read_u16 v15, v11 offset:18224
	ds_read_u16 v16, v11 offset:21760
	ds_read_u16 v17, v11 offset:22032
	ds_read_u16 v18, v11 offset:22304
	ds_read_u16 v11, v11 offset:22576
	v_and_b32_e32 v85, 15, v8
	v_lshrrev_b32_e32 v8, 4, v8
	v_lshlrev_b32_e32 v8, 10, v8
	v_lshl_or_b32 v8, v85, 3, v8
	v_ashrrev_i32_e32 v9, 31, v8
	v_lshl_add_u64 v[8:9], v[8:9], 1, v[6:7]
	global_store_dwordx4 v[8:9], v[2:5], off
	v_and_b32_e32 v85, 15, v0
	v_lshrrev_b32_e32 v8, 4, v0
	v_lshlrev_b32_e32 v8, 10, v8
	v_lshl_or_b32 v8, v85, 3, v8
	v_ashrrev_i32_e32 v0, 3, v42
	s_waitcnt lgkmcnt(0)
	v_lshl_or_b32 v5, v11, 16, v18
	v_lshlrev_b32_e32 v11, 1, v0
	v_add3_u32 v11, 32, v11, v10
	v_lshl_or_b32 v2, v13, 16, v12
	v_lshl_or_b32 v3, v15, 16, v14
	v_lshl_or_b32 v4, v17, 16, v16
	ds_read_u16 v12, v11 offset:17408
	ds_read_u16 v13, v11 offset:17680
	ds_read_u16 v14, v11 offset:17952
	ds_read_u16 v15, v11 offset:18224
	ds_read_u16 v16, v11 offset:21760
	ds_read_u16 v17, v11 offset:22032
	ds_read_u16 v18, v11 offset:22304
	ds_read_u16 v11, v11 offset:22576
	v_ashrrev_i32_e32 v9, 31, v8
	v_lshl_add_u64 v[8:9], v[8:9], 1, v[6:7]
	global_store_dwordx4 v[8:9], v[2:5], off
	v_and_b32_e32 v85, 15, v0
	v_lshrrev_b32_e32 v8, 4, v0
	v_lshlrev_b32_e32 v8, 10, v8
	v_lshl_or_b32 v8, v85, 3, v8
	v_ashrrev_i32_e32 v0, 3, v43
	s_waitcnt lgkmcnt(0)
	v_lshl_or_b32 v5, v11, 16, v18
	v_lshlrev_b32_e32 v11, 1, v0
	v_add3_u32 v10, 32, v11, v10
	v_lshl_or_b32 v2, v13, 16, v12
	v_lshl_or_b32 v3, v15, 16, v14
	v_lshl_or_b32 v4, v17, 16, v16
	ds_read_u16 v11, v10 offset:17408
	ds_read_u16 v12, v10 offset:17680
	ds_read_u16 v13, v10 offset:17952
	ds_read_u16 v14, v10 offset:18224
	ds_read_u16 v15, v10 offset:21760
	ds_read_u16 v16, v10 offset:22032
	ds_read_u16 v17, v10 offset:22304
	ds_read_u16 v10, v10 offset:22576
	v_ashrrev_i32_e32 v9, 31, v8
	v_lshl_add_u64 v[8:9], v[8:9], 1, v[6:7]
	global_store_dwordx4 v[8:9], v[2:5], off
	v_and_b32_e32 v85, 15, v0
	v_lshrrev_b32_e32 v8, 4, v0
	v_lshlrev_b32_e32 v8, 10, v8
	v_lshl_or_b32 v8, v85, 3, v8
	v_ashrrev_i32_e32 v9, 31, v8
	s_waitcnt lgkmcnt(6)
	v_lshl_or_b32 v2, v12, 16, v11
	s_waitcnt lgkmcnt(4)
	v_lshl_or_b32 v3, v14, 16, v13
	s_waitcnt lgkmcnt(2)
	v_lshl_or_b32 v4, v16, 16, v15
	s_waitcnt lgkmcnt(0)
	v_lshl_or_b32 v5, v10, 16, v17
	v_lshl_add_u64 v[6:7], v[8:9], 1, v[6:7]
	s_add_i32 s0, 32, 0x11000
	global_store_dwordx4 v[6:7], v[2:5], off
	v_and_b32_e32 v10, 63, v34
	v_lshrrev_b32_e32 v11, 6, v34
	v_and_b32_e32 v12, 15, v10
	v_lshrrev_b32_e32 v13, 4, v10
	s_lshl_b32 s62, s7, 1
	s_nop 0
	v_readfirstlane_b32 s0, v11
	s_nop 3
	s_mul_i32 s1, s0, 4416
	v_mov_b32_e32 v14, s1
	v_cmp_eq_u32_e32 vcc, 0, v12
	v_cndmask_b32_e64 v16, 0, 1.0, vcc
	v_cmp_eq_u32_e32 vcc, 1, v12
	v_cndmask_b32_e64 v17, 0, 1.0, vcc
	v_cmp_eq_u32_e32 vcc, 2, v12
	v_cndmask_b32_e64 v18, 0, 1.0, vcc
	v_cmp_eq_u32_e32 vcc, 3, v12
	v_cndmask_b32_e64 v19, 0, 1.0, vcc
	v_cmp_eq_u32_e32 vcc, 4, v12
	v_cndmask_b32_e64 v20, 0, 1.0, vcc
	v_cmp_eq_u32_e32 vcc, 5, v12
	v_cndmask_b32_e64 v21, 0, 1.0, vcc
	v_cmp_eq_u32_e32 vcc, 6, v12
	v_cndmask_b32_e64 v22, 0, 1.0, vcc
	v_cmp_eq_u32_e32 vcc, 7, v12
	v_cndmask_b32_e64 v23, 0, 1.0, vcc
	v_cmp_eq_u32_e32 vcc, 8, v12
	v_cndmask_b32_e64 v24, 0, 1.0, vcc
	v_cmp_eq_u32_e32 vcc, 9, v12
	v_cndmask_b32_e64 v25, 0, 1.0, vcc
	v_cmp_eq_u32_e32 vcc, 10, v12
	v_cndmask_b32_e64 v26, 0, 1.0, vcc
	v_cmp_eq_u32_e32 vcc, 11, v12
	v_cndmask_b32_e64 v27, 0, 1.0, vcc
	v_cmp_eq_u32_e32 vcc, 12, v12
	v_cndmask_b32_e64 v28, 0, 1.0, vcc
	v_cmp_eq_u32_e32 vcc, 13, v12
	v_cndmask_b32_e64 v29, 0, 1.0, vcc
	v_cmp_eq_u32_e32 vcc, 14, v12
	v_cndmask_b32_e64 v30, 0, 1.0, vcc
	v_cmp_eq_u32_e32 vcc, 15, v12
	v_cndmask_b32_e64 v31, 0, 1.0, vcc
	ds_read_b128 v[52:55], v14 offset:52528
	ds_read_b128 v[36:39], v14 offset:52800
	s_waitcnt lgkmcnt(1)
	v_fma_f32 v17, -v52, v16, v17
	ds_read_b128 v[52:55], v14 offset:53072
	s_waitcnt lgkmcnt(1)
	v_fma_f32 v18, -v36, v16, v18
	v_fma_f32 v18, -v37, v17, v18
	ds_read_b128 v[36:39], v14 offset:53344
	s_waitcnt lgkmcnt(1)
	v_fma_f32 v19, -v52, v16, v19
	v_fma_f32 v19, -v53, v17, v19
	v_fma_f32 v19, -v54, v18, v19
	ds_read_b128 v[52:55], v14 offset:53616
	ds_read_b128 v[56:59], v14 offset:53632
	s_waitcnt lgkmcnt(2)
; DEVI float bf2f(bf16_t b) { return __uint_as_float(((unsigned)b) << 16); }
; DEVI void prep_item(const Params& p, int j, int n, int h, char* smem) {
;     ...
; #pragma unroll
;     for (int i = 0; i < 64; ++i) {
;       const float* amz = am + zero;
;       const float* sbz = sbeta + zero;
;       const float eg = __expf(sbz[64 + i]);
;       float acc = bf2f(*(const unsigned short*)(src + i * 272)) * sbz[i] * (isu ? 1.0f : eg);
; #pragma unroll
;       for (int j4 = 0; j4 < (i + 3) / 4; ++j4) {
;         const f32x4 a = *(const f32x4*)(amz + i * 68 + j4 * 4);
;         acc -= a[0] * x[j4 * 4 + 0];
;         acc -= a[1] * x[j4 * 4 + 1];
;         acc -= a[2] * x[j4 * 4 + 2];
;         acc -= a[3] * x[j4 * 4 + 3];
;       }
;       asm volatile("" : "+v"(zero), "+v"(acc));
;       x[i] = acc;
;     }
	v_fma_f32 v20, -v36, v16, v20
	v_fma_f32 v20, -v37, v17, v20
	v_fma_f32 v20, -v38, v18, v20
	v_fma_f32 v20, -v39, v19, v20
	ds_read_b128 v[36:39], v14 offset:53888
	ds_read_b128 v[40:43], v14 offset:53904
	s_waitcnt lgkmcnt(2)
	v_fma_f32 v21, -v52, v16, v21
	v_fma_f32 v21, -v53, v17, v21
	v_fma_f32 v21, -v54, v18, v21
	v_fma_f32 v21, -v55, v19, v21
	v_fma_f32 v21, -v56, v20, v21
	ds_read_b128 v[52:55], v14 offset:54160
	ds_read_b128 v[56:59], v14 offset:54176
	s_waitcnt lgkmcnt(2)
	v_fma_f32 v22, -v36, v16, v22
	v_fma_f32 v22, -v37, v17, v22
	v_fma_f32 v22, -v38, v18, v22
	v_fma_f32 v22, -v39, v19, v22
	v_fma_f32 v22, -v40, v20, v22
	v_fma_f32 v22, -v41, v21, v22
	ds_read_b128 v[36:39], v14 offset:54432
	ds_read_b128 v[40:43], v14 offset:54448
	s_waitcnt lgkmcnt(2)
	v_fma_f32 v23, -v52, v16, v23
	v_fma_f32 v23, -v53, v17, v23
	v_fma_f32 v23, -v54, v18, v23
	v_fma_f32 v23, -v55, v19, v23
	v_fma_f32 v23, -v56, v20, v23
	v_fma_f32 v23, -v57, v21, v23
	v_fma_f32 v23, -v58, v22, v23
	ds_read_b128 v[52:55], v14 offset:54704
	ds_read_b128 v[56:59], v14 offset:54720
	ds_read_b128 v[60:63], v14 offset:54736
	s_waitcnt lgkmcnt(3)
	v_fma_f32 v24, -v36, v16, v24
	v_fma_f32 v24, -v37, v17, v24
	v_fma_f32 v24, -v38, v18, v24
	v_fma_f32 v24, -v39, v19, v24
	v_fma_f32 v24, -v40, v20, v24
	v_fma_f32 v24, -v41, v21, v24
	v_fma_f32 v24, -v42, v22, v24
	v_fma_f32 v24, -v43, v23, v24
	ds_read_b128 v[36:39], v14 offset:54976
	ds_read_b128 v[40:43], v14 offset:54992
	ds_read_b128 v[44:47], v14 offset:55008
	s_waitcnt lgkmcnt(3)
	v_fma_f32 v25, -v52, v16, v25
	v_fma_f32 v25, -v53, v17, v25
	v_fma_f32 v25, -v54, v18, v25
	v_fma_f32 v25, -v55, v19, v25
	v_fma_f32 v25, -v56, v20, v25
	v_fma_f32 v25, -v57, v21, v25
	v_fma_f32 v25, -v58, v22, v25
	v_fma_f32 v25, -v59, v23, v25
	v_fma_f32 v25, -v60, v24, v25
	ds_read_b128 v[52:55], v14 offset:55248
	ds_read_b128 v[56:59], v14 offset:55264
	ds_read_b128 v[60:63], v14 offset:55280
	s_waitcnt lgkmcnt(3)
	v_fma_f32 v26, -v36, v16, v26
	v_fma_f32 v26, -v37, v17, v26
	v_fma_f32 v26, -v38, v18, v26
	v_fma_f32 v26, -v39, v19, v26
	v_fma_f32 v26, -v40, v20, v26
	v_fma_f32 v26, -v41, v21, v26
	v_fma_f32 v26, -v42, v22, v26
	v_fma_f32 v26, -v43, v23, v26
	v_fma_f32 v26, -v44, v24, v26
	v_fma_f32 v26, -v45, v25, v26
	ds_read_b128 v[36:39], v14 offset:55520
	ds_read_b128 v[40:43], v14 offset:55536
	ds_read_b128 v[44:47], v14 offset:55552
	s_waitcnt lgkmcnt(3)
	v_fma_f32 v27, -v52, v16, v27
	v_fma_f32 v27, -v53, v17, v27
	v_fma_f32 v27, -v54, v18, v27
	v_fma_f32 v27, -v55, v19, v27
	v_fma_f32 v27, -v56, v20, v27
	v_fma_f32 v27, -v57, v21, v27
	v_fma_f32 v27, -v58, v22, v27
	v_fma_f32 v27, -v59, v23, v27
	v_fma_f32 v27, -v60, v24, v27
	v_fma_f32 v27, -v61, v25, v27
	v_fma_f32 v27, -v62, v26, v27
	ds_read_b128 v[52:55], v14 offset:55792
	ds_read_b128 v[56:59], v14 offset:55808
	ds_read_b128 v[60:63], v14 offset:55824
	ds_read_b128 v[64:67], v14 offset:55840
	s_waitcnt lgkmcnt(4)
	v_fma_f32 v28, -v36, v16, v28
	v_fma_f32 v28, -v37, v17, v28
	v_fma_f32 v28, -v38, v18, v28
	v_fma_f32 v28, -v39, v19, v28
	v_fma_f32 v28, -v40, v20, v28
	v_fma_f32 v28, -v41, v21, v28
	v_fma_f32 v28, -v42, v22, v28
	v_fma_f32 v28, -v43, v23, v28
	v_fma_f32 v28, -v44, v24, v28
	v_fma_f32 v28, -v45, v25, v28
	v_fma_f32 v28, -v46, v26, v28
	v_fma_f32 v28, -v47, v27, v28
	ds_read_b128 v[36:39], v14 offset:56064
	ds_read_b128 v[40:43], v14 offset:56080
	ds_read_b128 v[44:47], v14 offset:56096
	ds_read_b128 v[48:51], v14 offset:56112
	s_waitcnt lgkmcnt(4)
	v_fma_f32 v29, -v52, v16, v29
	v_fma_f32 v29, -v53, v17, v29
	v_fma_f32 v29, -v54, v18, v29
	v_fma_f32 v29, -v55, v19, v29
	v_fma_f32 v29, -v56, v20, v29
	v_fma_f32 v29, -v57, v21, v29
	v_fma_f32 v29, -v58, v22, v29
	v_fma_f32 v29, -v59, v23, v29
	v_fma_f32 v29, -v60, v24, v29
	v_fma_f32 v29, -v61, v25, v29
	v_fma_f32 v29, -v62, v26, v29
	v_fma_f32 v29, -v63, v27, v29
	v_fma_f32 v29, -v64, v28, v29
	ds_read_b128 v[52:55], v14 offset:56336
	ds_read_b128 v[56:59], v14 offset:56352
	ds_read_b128 v[60:63], v14 offset:56368
	ds_read_b128 v[64:67], v14 offset:56384
	s_waitcnt lgkmcnt(4)
	v_fma_f32 v30, -v36, v16, v30
	v_fma_f32 v30, -v37, v17, v30
	v_fma_f32 v30, -v38, v18, v30
	v_fma_f32 v30, -v39, v19, v30
	v_fma_f32 v30, -v40, v20, v30
	v_fma_f32 v30, -v41, v21, v30
	v_fma_f32 v30, -v42, v22, v30
	v_fma_f32 v30, -v43, v23, v30
	v_fma_f32 v30, -v44, v24, v30
	v_fma_f32 v30, -v45, v25, v30
	v_fma_f32 v30, -v46, v26, v30
	v_fma_f32 v30, -v47, v27, v30
	v_fma_f32 v30, -v48, v28, v30
	v_fma_f32 v30, -v49, v29, v30
	s_waitcnt lgkmcnt(0)
	v_fma_f32 v31, -v52, v16, v31
	v_fma_f32 v31, -v53, v17, v31
	v_fma_f32 v31, -v54, v18, v31
	v_fma_f32 v31, -v55, v19, v31
	v_fma_f32 v31, -v56, v20, v31
	v_fma_f32 v31, -v57, v21, v31
	v_fma_f32 v31, -v58, v22, v31
	v_fma_f32 v31, -v59, v23, v31
	v_fma_f32 v31, -v60, v24, v31
	v_fma_f32 v31, -v61, v25, v31
	v_fma_f32 v31, -v62, v26, v31
	v_fma_f32 v31, -v63, v27, v31
	v_fma_f32 v31, -v64, v28, v31
	v_fma_f32 v31, -v65, v29, v31
	v_fma_f32 v31, -v66, v30, v31
	s_lshl_b32 s1, s0, 10
	v_lshl_add_u32 v14, v12, 2, s1
	ds_write_b32 v14, v16 offset:32
	ds_write_b32 v14, v17 offset:96
	ds_write_b32 v14, v18 offset:160
	ds_write_b32 v14, v19 offset:224
	ds_write_b32 v14, v20 offset:288
	ds_write_b32 v14, v21 offset:352
	ds_write_b32 v14, v22 offset:416
	ds_write_b32 v14, v23 offset:480
	ds_write_b32 v14, v24 offset:544
	ds_write_b32 v14, v25 offset:608
	ds_write_b32 v14, v26 offset:672
	ds_write_b32 v14, v27 offset:736
	ds_write_b32 v14, v28 offset:800
	ds_write_b32 v14, v29 offset:864
	ds_write_b32 v14, v30 offset:928
	ds_write_b32 v14, v31 offset:992
	s_cmp_lt_u32 s0, 2
	s_mov_b32 s1, 17184
	s_cselect_b32 s1, 34848, s1
	s_lshl_b32 s7, s0, 7
	s_add_u32 s1, s1, s7
	v_lshlrev_b32_e32 v14, 1, v12
	v_mul_u32_u24_e32 v15, 1088, v13
	v_add3_u32 v14, v14, v15, s1
	v_lshlrev_b32_e32 v15, 4, v13
	v_add_u32_e32 v15, 0x10000, v15
	ds_read_b128 v[16:19], v15 offset:4128
	ds_read_b128 v[20:23], v15 offset:4192
	ds_read_b128 v[24:27], v15 offset:4256
	ds_read_b128 v[28:31], v15 offset:4320
	s_cmp_lt_u32 s0, 2
	s_cbranch_scc1 .Lpp_fac_done
; DEVI float bf2f(bf16_t b) { return __uint_as_float(((unsigned)b) << 16); }
; DEVI void prep_item(const Params& p, int j, int n, int h, char* smem) {
;     ...
;   {
;     const int c = tid;
;     const bool isu = c < 128;
;     const char* src = isu ? (vs + c * 2) : (ks + (c - 128) * 2);
;     float x[64];
; #pragma unroll
;     for (int i = 0; i < 64; ++i) x[i] = 0.f;
;     int zero;
;     asm volatile("v_mov_b32 %0, 0" : "=v"(zero));
; #pragma unroll
;     for (int i = 0; i < 64; ++i) {
;       const float* amz = am + zero;
;       const float* sbz = sbeta + zero;
;       const float eg = __expf(sbz[64 + i]);
;       float acc = bf2f(*(const unsigned short*)(src + i * 272)) * sbz[i] * (isu ? 1.0f : eg);
; #pragma unroll
;       for (int j4 = 0; j4 < (i + 3) / 4; ++j4) {
;         const f32x4 a = *(const f32x4*)(amz + i * 68 + j4 * 4);
;         acc -= a[0] * x[j4 * 4 + 0];
;         acc -= a[1] * x[j4 * 4 + 1];
;         acc -= a[2] * x[j4 * 4 + 2];
;         acc -= a[3] * x[j4 * 4 + 3];
;       }
;       asm volatile("" : "+v"(zero), "+v"(acc));
;       x[i] = acc;
;     }
	ds_read_b128 v[2:5], v15 offset:4384
	s_waitcnt lgkmcnt(0)
	v_mul_f32_e32 v2, 0x3fb8aa3b, v2
	v_mul_f32_e32 v3, 0x3fb8aa3b, v3
	v_mul_f32_e32 v4, 0x3fb8aa3b, v4
	v_mul_f32_e32 v5, 0x3fb8aa3b, v5
	v_exp_f32_e32 v2, v2
	v_exp_f32_e32 v3, v3
	v_exp_f32_e32 v4, v4
	v_exp_f32_e32 v5, v5
	s_nop 0
	v_mov_b32_e32 v164, v2
	v_mov_b32_e32 v165, v3
	v_mov_b32_e32 v166, v4
	v_mov_b32_e32 v167, v5
	ds_read_b128 v[6:9], v15 offset:4448
	s_waitcnt lgkmcnt(0)
	v_mul_f32_e32 v6, 0x3fb8aa3b, v6
	v_mul_f32_e32 v7, 0x3fb8aa3b, v7
	v_mul_f32_e32 v8, 0x3fb8aa3b, v8
	v_mul_f32_e32 v9, 0x3fb8aa3b, v9
	v_exp_f32_e32 v6, v6
	v_exp_f32_e32 v7, v7
	v_exp_f32_e32 v8, v8
	v_exp_f32_e32 v9, v9
	s_nop 0
	v_mov_b32_e32 v168, v6
	v_mov_b32_e32 v169, v7
	v_mov_b32_e32 v170, v8
	v_mov_b32_e32 v171, v9
	ds_read_b128 v[2:5], v15 offset:4512
	s_waitcnt lgkmcnt(0)
	v_mul_f32_e32 v2, 0x3fb8aa3b, v2
	v_mul_f32_e32 v3, 0x3fb8aa3b, v3
	v_mul_f32_e32 v4, 0x3fb8aa3b, v4
	v_mul_f32_e32 v5, 0x3fb8aa3b, v5
	v_exp_f32_e32 v2, v2
	v_exp_f32_e32 v3, v3
	v_exp_f32_e32 v4, v4
	v_exp_f32_e32 v5, v5
	s_nop 0
	v_mov_b32_e32 v172, v2
	v_mov_b32_e32 v173, v3
	v_mov_b32_e32 v174, v4
	v_mov_b32_e32 v175, v5
	ds_read_b128 v[6:9], v15 offset:4576
	s_waitcnt lgkmcnt(0)
	v_mul_f32_e32 v6, 0x3fb8aa3b, v6
	v_mul_f32_e32 v7, 0x3fb8aa3b, v7
	v_mul_f32_e32 v8, 0x3fb8aa3b, v8
	v_mul_f32_e32 v9, 0x3fb8aa3b, v9
	v_exp_f32_e32 v6, v6
	v_exp_f32_e32 v7, v7
	v_exp_f32_e32 v8, v8
	v_exp_f32_e32 v9, v9
	s_nop 0
	v_mov_b32_e32 v176, v6
	v_mov_b32_e32 v177, v7
	v_mov_b32_e32 v178, v8
	v_mov_b32_e32 v179, v9
.Lpp_fac_done:
	s_waitcnt lgkmcnt(0)
	ds_read_u16 v100, v14 offset:0
	ds_read_u16 v101, v14 offset:272
	ds_read_u16 v102, v14 offset:544
	ds_read_u16 v103, v14 offset:816
	ds_read_u16 v116, v14 offset:4352
	ds_read_u16 v117, v14 offset:4624
	ds_read_u16 v118, v14 offset:4896
	ds_read_u16 v119, v14 offset:5168
	ds_read_u16 v132, v14 offset:8704
	ds_read_u16 v133, v14 offset:8976
	ds_read_u16 v134, v14 offset:9248
	ds_read_u16 v135, v14 offset:9520
	s_waitcnt lgkmcnt(8)
	v_lshlrev_b32_e32 v100, 16, v100
	v_lshlrev_b32_e32 v101, 16, v101
	v_lshlrev_b32_e32 v102, 16, v102
	v_lshlrev_b32_e32 v103, 16, v103
	v_mul_f32_e32 v100, v16, v100
	v_mul_f32_e32 v101, v17, v101
	v_mul_f32_e32 v102, v18, v102
	v_mul_f32_e32 v103, v19, v103
	ds_read_u16 v148, v14 offset:13056
	ds_read_u16 v149, v14 offset:13328
	ds_read_u16 v150, v14 offset:13600
	ds_read_u16 v151, v14 offset:13872
	s_waitcnt lgkmcnt(8)
	v_lshlrev_b32_e32 v116, 16, v116
	v_lshlrev_b32_e32 v117, 16, v117
	v_lshlrev_b32_e32 v118, 16, v118
	v_lshlrev_b32_e32 v119, 16, v119
	v_mul_f32_e32 v116, v20, v116
	v_mul_f32_e32 v117, v21, v117
	v_mul_f32_e32 v118, v22, v118
	v_mul_f32_e32 v119, v23, v119
	ds_read_u16 v104, v14 offset:32
	ds_read_u16 v105, v14 offset:304
	ds_read_u16 v106, v14 offset:576
	ds_read_u16 v107, v14 offset:848
	s_waitcnt lgkmcnt(8)
	v_lshlrev_b32_e32 v132, 16, v132
	v_lshlrev_b32_e32 v133, 16, v133
	v_lshlrev_b32_e32 v134, 16, v134
	v_lshlrev_b32_e32 v135, 16, v135
	v_mul_f32_e32 v132, v24, v132
	v_mul_f32_e32 v133, v25, v133
	v_mul_f32_e32 v134, v26, v134
	v_mul_f32_e32 v135, v27, v135
	ds_read_u16 v120, v14 offset:4384
	ds_read_u16 v121, v14 offset:4656
	ds_read_u16 v122, v14 offset:4928
	ds_read_u16 v123, v14 offset:5200
	s_waitcnt lgkmcnt(8)
	v_lshlrev_b32_e32 v148, 16, v148
	v_lshlrev_b32_e32 v149, 16, v149
	v_lshlrev_b32_e32 v150, 16, v150
	v_lshlrev_b32_e32 v151, 16, v151
	v_mul_f32_e32 v148, v28, v148
	v_mul_f32_e32 v149, v29, v149
	v_mul_f32_e32 v150, v30, v150
	v_mul_f32_e32 v151, v31, v151
	ds_read_u16 v136, v14 offset:8736
	ds_read_u16 v137, v14 offset:9008
	ds_read_u16 v138, v14 offset:9280
	ds_read_u16 v139, v14 offset:9552
	s_waitcnt lgkmcnt(8)
	v_lshlrev_b32_e32 v104, 16, v104
	v_lshlrev_b32_e32 v105, 16, v105
	v_lshlrev_b32_e32 v106, 16, v106
	v_lshlrev_b32_e32 v107, 16, v107
	v_mul_f32_e32 v104, v16, v104
	v_mul_f32_e32 v105, v17, v105
	v_mul_f32_e32 v106, v18, v106
	v_mul_f32_e32 v107, v19, v107
	ds_read_u16 v152, v14 offset:13088
	ds_read_u16 v153, v14 offset:13360
	ds_read_u16 v154, v14 offset:13632
	ds_read_u16 v155, v14 offset:13904
	s_waitcnt lgkmcnt(8)
	v_lshlrev_b32_e32 v120, 16, v120
	v_lshlrev_b32_e32 v121, 16, v121
	v_lshlrev_b32_e32 v122, 16, v122
	v_lshlrev_b32_e32 v123, 16, v123
	v_mul_f32_e32 v120, v20, v120
	v_mul_f32_e32 v121, v21, v121
	v_mul_f32_e32 v122, v22, v122
	v_mul_f32_e32 v123, v23, v123
	ds_read_u16 v108, v14 offset:64
	ds_read_u16 v109, v14 offset:336
	ds_read_u16 v110, v14 offset:608
	ds_read_u16 v111, v14 offset:880
	s_waitcnt lgkmcnt(8)
	v_lshlrev_b32_e32 v136, 16, v136
	v_lshlrev_b32_e32 v137, 16, v137
	v_lshlrev_b32_e32 v138, 16, v138
	v_lshlrev_b32_e32 v139, 16, v139
	v_mul_f32_e32 v136, v24, v136
	v_mul_f32_e32 v137, v25, v137
	v_mul_f32_e32 v138, v26, v138
	v_mul_f32_e32 v139, v27, v139
	ds_read_u16 v124, v14 offset:4416
	ds_read_u16 v125, v14 offset:4688
	ds_read_u16 v126, v14 offset:4960
	ds_read_u16 v127, v14 offset:5232
	s_waitcnt lgkmcnt(8)
	v_lshlrev_b32_e32 v152, 16, v152
	v_lshlrev_b32_e32 v153, 16, v153
	v_lshlrev_b32_e32 v154, 16, v154
	v_lshlrev_b32_e32 v155, 16, v155
	v_mul_f32_e32 v152, v28, v152
	v_mul_f32_e32 v153, v29, v153
	v_mul_f32_e32 v154, v30, v154
	v_mul_f32_e32 v155, v31, v155
	ds_read_u16 v140, v14 offset:8768
	ds_read_u16 v141, v14 offset:9040
	ds_read_u16 v142, v14 offset:9312
	ds_read_u16 v143, v14 offset:9584
	s_waitcnt lgkmcnt(8)
	v_lshlrev_b32_e32 v108, 16, v108
	v_lshlrev_b32_e32 v109, 16, v109
	v_lshlrev_b32_e32 v110, 16, v110
	v_lshlrev_b32_e32 v111, 16, v111
	v_mul_f32_e32 v108, v16, v108
	v_mul_f32_e32 v109, v17, v109
	v_mul_f32_e32 v110, v18, v110
	v_mul_f32_e32 v111, v19, v111
	ds_read_u16 v156, v14 offset:13120
	ds_read_u16 v157, v14 offset:13392
	ds_read_u16 v158, v14 offset:13664
	ds_read_u16 v159, v14 offset:13936
	s_waitcnt lgkmcnt(8)
; DEVI float bf2f(bf16_t b) { return __uint_as_float(((unsigned)b) << 16); }
; DEVI void prep_item(const Params& p, int j, int n, int h, char* smem) {
;     ...
;     for (int i = 0; i < 64; ++i) {
;       const float* amz = am + zero;
;       const float* sbz = sbeta + zero;
;       const float eg = __expf(sbz[64 + i]);
;       float acc = bf2f(*(const unsigned short*)(src + i * 272)) * sbz[i] * (isu ? 1.0f : eg);
	v_lshlrev_b32_e32 v124, 16, v124
	v_lshlrev_b32_e32 v125, 16, v125
	v_lshlrev_b32_e32 v126, 16, v126
	v_lshlrev_b32_e32 v127, 16, v127
	v_mul_f32_e32 v124, v20, v124
	v_mul_f32_e32 v125, v21, v125
	v_mul_f32_e32 v126, v22, v126
	v_mul_f32_e32 v127, v23, v127
	ds_read_u16 v112, v14 offset:96
	ds_read_u16 v113, v14 offset:368
	ds_read_u16 v114, v14 offset:640
	ds_read_u16 v115, v14 offset:912
	s_waitcnt lgkmcnt(8)
	v_lshlrev_b32_e32 v140, 16, v140
	v_lshlrev_b32_e32 v141, 16, v141
	v_lshlrev_b32_e32 v142, 16, v142
	v_lshlrev_b32_e32 v143, 16, v143
	v_mul_f32_e32 v140, v24, v140
	v_mul_f32_e32 v141, v25, v141
	v_mul_f32_e32 v142, v26, v142
	v_mul_f32_e32 v143, v27, v143
	ds_read_u16 v128, v14 offset:4448
	ds_read_u16 v129, v14 offset:4720
	ds_read_u16 v130, v14 offset:4992
	ds_read_u16 v131, v14 offset:5264
	s_waitcnt lgkmcnt(8)
	v_lshlrev_b32_e32 v156, 16, v156
	v_lshlrev_b32_e32 v157, 16, v157
	v_lshlrev_b32_e32 v158, 16, v158
	v_lshlrev_b32_e32 v159, 16, v159
	v_mul_f32_e32 v156, v28, v156
	v_mul_f32_e32 v157, v29, v157
	v_mul_f32_e32 v158, v30, v158
	v_mul_f32_e32 v159, v31, v159
	ds_read_u16 v144, v14 offset:8800
	ds_read_u16 v145, v14 offset:9072
	ds_read_u16 v146, v14 offset:9344
	ds_read_u16 v147, v14 offset:9616
	s_waitcnt lgkmcnt(8)
	v_lshlrev_b32_e32 v112, 16, v112
	v_lshlrev_b32_e32 v113, 16, v113
	v_lshlrev_b32_e32 v114, 16, v114
	v_lshlrev_b32_e32 v115, 16, v115
	v_mul_f32_e32 v112, v16, v112
	v_mul_f32_e32 v113, v17, v113
	v_mul_f32_e32 v114, v18, v114
	v_mul_f32_e32 v115, v19, v115
	ds_read_u16 v160, v14 offset:13152
	ds_read_u16 v161, v14 offset:13424
	ds_read_u16 v162, v14 offset:13696
	ds_read_u16 v163, v14 offset:13968
	s_waitcnt lgkmcnt(8)
	v_lshlrev_b32_e32 v128, 16, v128
	v_lshlrev_b32_e32 v129, 16, v129
	v_lshlrev_b32_e32 v130, 16, v130
	v_lshlrev_b32_e32 v131, 16, v131
	v_mul_f32_e32 v128, v20, v128
	v_mul_f32_e32 v129, v21, v129
	v_mul_f32_e32 v130, v22, v130
	v_mul_f32_e32 v131, v23, v131
	s_waitcnt lgkmcnt(4)
	v_lshlrev_b32_e32 v144, 16, v144
	v_lshlrev_b32_e32 v145, 16, v145
	v_lshlrev_b32_e32 v146, 16, v146
	v_lshlrev_b32_e32 v147, 16, v147
	v_mul_f32_e32 v144, v24, v144
	v_mul_f32_e32 v145, v25, v145
	v_mul_f32_e32 v146, v26, v146
	v_mul_f32_e32 v147, v27, v147
	s_waitcnt lgkmcnt(0)
	v_lshlrev_b32_e32 v160, 16, v160
	v_lshlrev_b32_e32 v161, 16, v161
	v_lshlrev_b32_e32 v162, 16, v162
	v_lshlrev_b32_e32 v163, 16, v163
	v_mul_f32_e32 v160, v28, v160
	v_mul_f32_e32 v161, v29, v161
	v_mul_f32_e32 v162, v30, v162
	v_mul_f32_e32 v163, v31, v163
	s_cmp_lt_u32 s0, 2
	s_cbranch_scc1 .Lpp_rhs_done
	v_mul_f32_e32 v100, v164, v100
	v_mul_f32_e32 v101, v165, v101
	v_mul_f32_e32 v102, v166, v102
	v_mul_f32_e32 v103, v167, v103
	v_mul_f32_e32 v116, v168, v116
	v_mul_f32_e32 v117, v169, v117
	v_mul_f32_e32 v118, v170, v118
	v_mul_f32_e32 v119, v171, v119
	v_mul_f32_e32 v132, v172, v132
	v_mul_f32_e32 v133, v173, v133
	v_mul_f32_e32 v134, v174, v134
	v_mul_f32_e32 v135, v175, v135
	v_mul_f32_e32 v148, v176, v148
	v_mul_f32_e32 v149, v177, v149
	v_mul_f32_e32 v150, v178, v150
	v_mul_f32_e32 v151, v179, v151
	v_mul_f32_e32 v104, v164, v104
	v_mul_f32_e32 v105, v165, v105
	v_mul_f32_e32 v106, v166, v106
	v_mul_f32_e32 v107, v167, v107
	v_mul_f32_e32 v120, v168, v120
	v_mul_f32_e32 v121, v169, v121
	v_mul_f32_e32 v122, v170, v122
	v_mul_f32_e32 v123, v171, v123
	v_mul_f32_e32 v136, v172, v136
	v_mul_f32_e32 v137, v173, v137
	v_mul_f32_e32 v138, v174, v138
	v_mul_f32_e32 v139, v175, v139
	v_mul_f32_e32 v152, v176, v152
	v_mul_f32_e32 v153, v177, v153
	v_mul_f32_e32 v154, v178, v154
	v_mul_f32_e32 v155, v179, v155
	v_mul_f32_e32 v108, v164, v108
	v_mul_f32_e32 v109, v165, v109
	v_mul_f32_e32 v110, v166, v110
	v_mul_f32_e32 v111, v167, v111
	v_mul_f32_e32 v124, v168, v124
	v_mul_f32_e32 v125, v169, v125
	v_mul_f32_e32 v126, v170, v126
	v_mul_f32_e32 v127, v171, v127
	v_mul_f32_e32 v140, v172, v140
	v_mul_f32_e32 v141, v173, v141
	v_mul_f32_e32 v142, v174, v142
	v_mul_f32_e32 v143, v175, v143
	v_mul_f32_e32 v156, v176, v156
	v_mul_f32_e32 v157, v177, v157
	v_mul_f32_e32 v158, v178, v158
	v_mul_f32_e32 v159, v179, v159
	v_mul_f32_e32 v112, v164, v112
	v_mul_f32_e32 v113, v165, v113
	v_mul_f32_e32 v114, v166, v114
	v_mul_f32_e32 v115, v167, v115
	v_mul_f32_e32 v128, v168, v128
	v_mul_f32_e32 v129, v169, v129
	v_mul_f32_e32 v130, v170, v130
	v_mul_f32_e32 v131, v171, v131
	v_mul_f32_e32 v144, v172, v144
	v_mul_f32_e32 v145, v173, v145
	v_mul_f32_e32 v146, v174, v146
	v_mul_f32_e32 v147, v175, v147
	v_mul_f32_e32 v160, v176, v160
	v_mul_f32_e32 v161, v177, v161
	v_mul_f32_e32 v162, v178, v162
	v_mul_f32_e32 v163, v179, v163
; DEVI void prep_item(const Params& p, int j, int n, int h, char* smem) {
;     ...
; #pragma unroll
;       for (int j4 = 0; j4 < (i + 3) / 4; ++j4) {
;         const f32x4 a = *(const f32x4*)(amz + i * 68 + j4 * 4);
;         acc -= a[0] * x[j4 * 4 + 0];
;         acc -= a[1] * x[j4 * 4 + 1];
;         acc -= a[2] * x[j4 * 4 + 2];
;         acc -= a[3] * x[j4 * 4 + 3];
;       }
;       asm volatile("" : "+v"(zero), "+v"(acc));
;       x[i] = acc;
;     }
.Lpp_rhs_done:
	s_waitcnt lgkmcnt(0)
	s_barrier
	v_mul_u32_u24_e32 v14, 272, v12
	v_lshl_add_u32 v14, v13, 4, v14
	v_lshlrev_b32_e32 v15, 6, v12
	v_lshl_add_u32 v15, v13, 4, v15
	ds_read_b128 v[24:27], v15 offset:32
	s_waitcnt lgkmcnt(0)
	s_nop 7
	s_nop 7
	v_mfma_f32_16x16x4_f32 v[36:39], v24, v100, 0
	v_mfma_f32_16x16x4_f32 v[40:43], v24, v104, 0
	v_mfma_f32_16x16x4_f32 v[44:47], v24, v108, 0
	v_mfma_f32_16x16x4_f32 v[48:51], v24, v112, 0
	v_mfma_f32_16x16x4_f32 v[36:39], v25, v101, v[36:39]
	v_mfma_f32_16x16x4_f32 v[40:43], v25, v105, v[40:43]
	v_mfma_f32_16x16x4_f32 v[44:47], v25, v109, v[44:47]
	v_mfma_f32_16x16x4_f32 v[48:51], v25, v113, v[48:51]
	v_mfma_f32_16x16x4_f32 v[36:39], v26, v102, v[36:39]
	v_mfma_f32_16x16x4_f32 v[40:43], v26, v106, v[40:43]
	v_mfma_f32_16x16x4_f32 v[44:47], v26, v110, v[44:47]
	v_mfma_f32_16x16x4_f32 v[48:51], v26, v114, v[48:51]
	v_mfma_f32_16x16x4_f32 v[36:39], v27, v103, v[36:39]
	v_mfma_f32_16x16x4_f32 v[40:43], v27, v107, v[40:43]
	v_mfma_f32_16x16x4_f32 v[44:47], v27, v111, v[44:47]
	v_mfma_f32_16x16x4_f32 v[48:51], v27, v115, v[48:51]
	s_nop 7
	s_nop 7
	ds_read_b128 v[2:5], v14 offset:56608
	s_waitcnt lgkmcnt(0)
	v_xor_b32_e32 v2, 0x80000000, v2
	v_xor_b32_e32 v3, 0x80000000, v3
	v_xor_b32_e32 v4, 0x80000000, v4
	v_xor_b32_e32 v5, 0x80000000, v5
	s_nop 1
	v_mfma_f32_16x16x4_f32 v[116:119], v2, v36, v[116:119]
	v_mfma_f32_16x16x4_f32 v[120:123], v2, v40, v[120:123]
	v_mfma_f32_16x16x4_f32 v[124:127], v2, v44, v[124:127]
	v_mfma_f32_16x16x4_f32 v[128:131], v2, v48, v[128:131]
	v_mfma_f32_16x16x4_f32 v[116:119], v3, v37, v[116:119]
	v_mfma_f32_16x16x4_f32 v[120:123], v3, v41, v[120:123]
	v_mfma_f32_16x16x4_f32 v[124:127], v3, v45, v[124:127]
	v_mfma_f32_16x16x4_f32 v[128:131], v3, v49, v[128:131]
	v_mfma_f32_16x16x4_f32 v[116:119], v4, v38, v[116:119]
	v_mfma_f32_16x16x4_f32 v[120:123], v4, v42, v[120:123]
	v_mfma_f32_16x16x4_f32 v[124:127], v4, v46, v[124:127]
	v_mfma_f32_16x16x4_f32 v[128:131], v4, v50, v[128:131]
	v_mfma_f32_16x16x4_f32 v[116:119], v5, v39, v[116:119]
	v_mfma_f32_16x16x4_f32 v[120:123], v5, v43, v[120:123]
	v_mfma_f32_16x16x4_f32 v[124:127], v5, v47, v[124:127]
	v_mfma_f32_16x16x4_f32 v[128:131], v5, v51, v[128:131]
	ds_read_b128 v[24:27], v15 offset:1056
	s_waitcnt lgkmcnt(0)
	s_nop 7
	s_nop 7
	v_mfma_f32_16x16x4_f32 v[52:55], v24, v116, 0
	v_mfma_f32_16x16x4_f32 v[56:59], v24, v120, 0
	v_mfma_f32_16x16x4_f32 v[60:63], v24, v124, 0
	v_mfma_f32_16x16x4_f32 v[64:67], v24, v128, 0
	v_mfma_f32_16x16x4_f32 v[52:55], v25, v117, v[52:55]
	v_mfma_f32_16x16x4_f32 v[56:59], v25, v121, v[56:59]
	v_mfma_f32_16x16x4_f32 v[60:63], v25, v125, v[60:63]
	v_mfma_f32_16x16x4_f32 v[64:67], v25, v129, v[64:67]
	v_mfma_f32_16x16x4_f32 v[52:55], v26, v118, v[52:55]
	v_mfma_f32_16x16x4_f32 v[56:59], v26, v122, v[56:59]
	v_mfma_f32_16x16x4_f32 v[60:63], v26, v126, v[60:63]
	v_mfma_f32_16x16x4_f32 v[64:67], v26, v130, v[64:67]
	v_mfma_f32_16x16x4_f32 v[52:55], v27, v119, v[52:55]
	v_mfma_f32_16x16x4_f32 v[56:59], v27, v123, v[56:59]
	v_mfma_f32_16x16x4_f32 v[60:63], v27, v127, v[60:63]
	v_mfma_f32_16x16x4_f32 v[64:67], v27, v131, v[64:67]
	s_nop 7
	s_nop 7
	ds_read_b128 v[6:9], v14 offset:60960
	s_waitcnt lgkmcnt(0)
	v_xor_b32_e32 v6, 0x80000000, v6
	v_xor_b32_e32 v7, 0x80000000, v7
	v_xor_b32_e32 v8, 0x80000000, v8
	v_xor_b32_e32 v9, 0x80000000, v9
	s_nop 1
	v_mfma_f32_16x16x4_f32 v[132:135], v6, v36, v[132:135]
	v_mfma_f32_16x16x4_f32 v[136:139], v6, v40, v[136:139]
	v_mfma_f32_16x16x4_f32 v[140:143], v6, v44, v[140:143]
	v_mfma_f32_16x16x4_f32 v[144:147], v6, v48, v[144:147]
	v_mfma_f32_16x16x4_f32 v[132:135], v7, v37, v[132:135]
	v_mfma_f32_16x16x4_f32 v[136:139], v7, v41, v[136:139]
	v_mfma_f32_16x16x4_f32 v[140:143], v7, v45, v[140:143]
	v_mfma_f32_16x16x4_f32 v[144:147], v7, v49, v[144:147]
	v_mfma_f32_16x16x4_f32 v[132:135], v8, v38, v[132:135]
	v_mfma_f32_16x16x4_f32 v[136:139], v8, v42, v[136:139]
	v_mfma_f32_16x16x4_f32 v[140:143], v8, v46, v[140:143]
	v_mfma_f32_16x16x4_f32 v[144:147], v8, v50, v[144:147]
	v_mfma_f32_16x16x4_f32 v[132:135], v9, v39, v[132:135]
	v_mfma_f32_16x16x4_f32 v[136:139], v9, v43, v[136:139]
	v_mfma_f32_16x16x4_f32 v[140:143], v9, v47, v[140:143]
	v_mfma_f32_16x16x4_f32 v[144:147], v9, v51, v[144:147]
	ds_read_b128 v[2:5], v14 offset:61024
	s_waitcnt lgkmcnt(0)
	v_xor_b32_e32 v2, 0x80000000, v2
	v_xor_b32_e32 v3, 0x80000000, v3
	v_xor_b32_e32 v4, 0x80000000, v4
	v_xor_b32_e32 v5, 0x80000000, v5
	s_nop 1
	v_mfma_f32_16x16x4_f32 v[132:135], v2, v52, v[132:135]
	v_mfma_f32_16x16x4_f32 v[136:139], v2, v56, v[136:139]
	v_mfma_f32_16x16x4_f32 v[140:143], v2, v60, v[140:143]
	v_mfma_f32_16x16x4_f32 v[144:147], v2, v64, v[144:147]
	v_mfma_f32_16x16x4_f32 v[132:135], v3, v53, v[132:135]
	v_mfma_f32_16x16x4_f32 v[136:139], v3, v57, v[136:139]
	v_mfma_f32_16x16x4_f32 v[140:143], v3, v61, v[140:143]
	v_mfma_f32_16x16x4_f32 v[144:147], v3, v65, v[144:147]
	v_mfma_f32_16x16x4_f32 v[132:135], v4, v54, v[132:135]
	v_mfma_f32_16x16x4_f32 v[136:139], v4, v58, v[136:139]
	v_mfma_f32_16x16x4_f32 v[140:143], v4, v62, v[140:143]
	v_mfma_f32_16x16x4_f32 v[144:147], v4, v66, v[144:147]
	v_mfma_f32_16x16x4_f32 v[132:135], v5, v55, v[132:135]
	v_mfma_f32_16x16x4_f32 v[136:139], v5, v59, v[136:139]
	v_mfma_f32_16x16x4_f32 v[140:143], v5, v63, v[140:143]
	v_mfma_f32_16x16x4_f32 v[144:147], v5, v67, v[144:147]
	ds_read_b128 v[24:27], v15 offset:2080
	s_waitcnt lgkmcnt(0)
; DEVI float bf2f(bf16_t b) { return __uint_as_float(((unsigned)b) << 16); }
; DEVI void prep_item(const Params& p, int j, int n, int h, char* smem) {
;     ...
;   {
;     const int c = tid;
;     const bool isu = c < 128;
;     const char* src = isu ? (vs + c * 2) : (ks + (c - 128) * 2);
;     float x[64];
; #pragma unroll
;     for (int i = 0; i < 64; ++i) x[i] = 0.f;
;     int zero;
;     asm volatile("v_mov_b32 %0, 0" : "=v"(zero));
; #pragma unroll
;     for (int i = 0; i < 64; ++i) {
;       const float* amz = am + zero;
;       const float* sbz = sbeta + zero;
;       const float eg = __expf(sbz[64 + i]);
;       float acc = bf2f(*(const unsigned short*)(src + i * 272)) * sbz[i] * (isu ? 1.0f : eg);
; #pragma unroll
;       for (int j4 = 0; j4 < (i + 3) / 4; ++j4) {
;         const f32x4 a = *(const f32x4*)(amz + i * 68 + j4 * 4);
;         acc -= a[0] * x[j4 * 4 + 0];
;         acc -= a[1] * x[j4 * 4 + 1];
;         acc -= a[2] * x[j4 * 4 + 2];
;         acc -= a[3] * x[j4 * 4 + 3];
;       }
;       asm volatile("" : "+v"(zero), "+v"(acc));
;       x[i] = acc;
;     }
	s_nop 7
	s_nop 7
	v_mfma_f32_16x16x4_f32 v[68:71], v24, v132, 0
	v_mfma_f32_16x16x4_f32 v[72:75], v24, v136, 0
	v_mfma_f32_16x16x4_f32 v[76:79], v24, v140, 0
	v_mfma_f32_16x16x4_f32 v[80:83], v24, v144, 0
	v_mfma_f32_16x16x4_f32 v[68:71], v25, v133, v[68:71]
	v_mfma_f32_16x16x4_f32 v[72:75], v25, v137, v[72:75]
	v_mfma_f32_16x16x4_f32 v[76:79], v25, v141, v[76:79]
	v_mfma_f32_16x16x4_f32 v[80:83], v25, v145, v[80:83]
	v_mfma_f32_16x16x4_f32 v[68:71], v26, v134, v[68:71]
	v_mfma_f32_16x16x4_f32 v[72:75], v26, v138, v[72:75]
	v_mfma_f32_16x16x4_f32 v[76:79], v26, v142, v[76:79]
	v_mfma_f32_16x16x4_f32 v[80:83], v26, v146, v[80:83]
	v_mfma_f32_16x16x4_f32 v[68:71], v27, v135, v[68:71]
	v_mfma_f32_16x16x4_f32 v[72:75], v27, v139, v[72:75]
	v_mfma_f32_16x16x4_f32 v[76:79], v27, v143, v[76:79]
	v_mfma_f32_16x16x4_f32 v[80:83], v27, v147, v[80:83]
	s_nop 7
	s_nop 7
	ds_read_b128 v[6:9], v14 offset:65312
	s_waitcnt lgkmcnt(0)
	v_xor_b32_e32 v6, 0x80000000, v6
	v_xor_b32_e32 v7, 0x80000000, v7
	v_xor_b32_e32 v8, 0x80000000, v8
	v_xor_b32_e32 v9, 0x80000000, v9
	s_nop 1
	v_mfma_f32_16x16x4_f32 v[148:151], v6, v36, v[148:151]
	v_mfma_f32_16x16x4_f32 v[152:155], v6, v40, v[152:155]
	v_mfma_f32_16x16x4_f32 v[156:159], v6, v44, v[156:159]
	v_mfma_f32_16x16x4_f32 v[160:163], v6, v48, v[160:163]
	v_mfma_f32_16x16x4_f32 v[148:151], v7, v37, v[148:151]
	v_mfma_f32_16x16x4_f32 v[152:155], v7, v41, v[152:155]
	v_mfma_f32_16x16x4_f32 v[156:159], v7, v45, v[156:159]
	v_mfma_f32_16x16x4_f32 v[160:163], v7, v49, v[160:163]
	v_mfma_f32_16x16x4_f32 v[148:151], v8, v38, v[148:151]
	v_mfma_f32_16x16x4_f32 v[152:155], v8, v42, v[152:155]
	v_mfma_f32_16x16x4_f32 v[156:159], v8, v46, v[156:159]
	v_mfma_f32_16x16x4_f32 v[160:163], v8, v50, v[160:163]
	v_mfma_f32_16x16x4_f32 v[148:151], v9, v39, v[148:151]
	v_mfma_f32_16x16x4_f32 v[152:155], v9, v43, v[152:155]
	v_mfma_f32_16x16x4_f32 v[156:159], v9, v47, v[156:159]
	v_mfma_f32_16x16x4_f32 v[160:163], v9, v51, v[160:163]
	ds_read_b128 v[2:5], v14 offset:65376
	s_waitcnt lgkmcnt(0)
	v_xor_b32_e32 v2, 0x80000000, v2
	v_xor_b32_e32 v3, 0x80000000, v3
	v_xor_b32_e32 v4, 0x80000000, v4
	v_xor_b32_e32 v5, 0x80000000, v5
	s_nop 1
	v_mfma_f32_16x16x4_f32 v[148:151], v2, v52, v[148:151]
	v_mfma_f32_16x16x4_f32 v[152:155], v2, v56, v[152:155]
	v_mfma_f32_16x16x4_f32 v[156:159], v2, v60, v[156:159]
	v_mfma_f32_16x16x4_f32 v[160:163], v2, v64, v[160:163]
	v_mfma_f32_16x16x4_f32 v[148:151], v3, v53, v[148:151]
	v_mfma_f32_16x16x4_f32 v[152:155], v3, v57, v[152:155]
	v_mfma_f32_16x16x4_f32 v[156:159], v3, v61, v[156:159]
	v_mfma_f32_16x16x4_f32 v[160:163], v3, v65, v[160:163]
	v_mfma_f32_16x16x4_f32 v[148:151], v4, v54, v[148:151]
	v_mfma_f32_16x16x4_f32 v[152:155], v4, v58, v[152:155]
	v_mfma_f32_16x16x4_f32 v[156:159], v4, v62, v[156:159]
	v_mfma_f32_16x16x4_f32 v[160:163], v4, v66, v[160:163]
	v_mfma_f32_16x16x4_f32 v[148:151], v5, v55, v[148:151]
	v_mfma_f32_16x16x4_f32 v[152:155], v5, v59, v[152:155]
	v_mfma_f32_16x16x4_f32 v[156:159], v5, v63, v[156:159]
	v_mfma_f32_16x16x4_f32 v[160:163], v5, v67, v[160:163]
	ds_read_b128 v[6:9], v14 offset:65440
	s_waitcnt lgkmcnt(0)
	v_xor_b32_e32 v6, 0x80000000, v6
	v_xor_b32_e32 v7, 0x80000000, v7
	v_xor_b32_e32 v8, 0x80000000, v8
	v_xor_b32_e32 v9, 0x80000000, v9
	s_nop 1
	v_mfma_f32_16x16x4_f32 v[148:151], v6, v68, v[148:151]
	v_mfma_f32_16x16x4_f32 v[152:155], v6, v72, v[152:155]
	v_mfma_f32_16x16x4_f32 v[156:159], v6, v76, v[156:159]
	v_mfma_f32_16x16x4_f32 v[160:163], v6, v80, v[160:163]
	v_mfma_f32_16x16x4_f32 v[148:151], v7, v69, v[148:151]
	v_mfma_f32_16x16x4_f32 v[152:155], v7, v73, v[152:155]
	v_mfma_f32_16x16x4_f32 v[156:159], v7, v77, v[156:159]
	v_mfma_f32_16x16x4_f32 v[160:163], v7, v81, v[160:163]
	v_mfma_f32_16x16x4_f32 v[148:151], v8, v70, v[148:151]
	v_mfma_f32_16x16x4_f32 v[152:155], v8, v74, v[152:155]
	v_mfma_f32_16x16x4_f32 v[156:159], v8, v78, v[156:159]
	v_mfma_f32_16x16x4_f32 v[160:163], v8, v82, v[160:163]
	v_mfma_f32_16x16x4_f32 v[148:151], v9, v71, v[148:151]
	v_mfma_f32_16x16x4_f32 v[152:155], v9, v75, v[152:155]
	v_mfma_f32_16x16x4_f32 v[156:159], v9, v79, v[156:159]
	v_mfma_f32_16x16x4_f32 v[160:163], v9, v83, v[160:163]
	ds_read_b128 v[24:27], v15 offset:3104
	s_waitcnt lgkmcnt(0)
	s_nop 7
	s_nop 7
	v_mfma_f32_16x16x4_f32 v[84:87], v24, v148, 0
	v_mfma_f32_16x16x4_f32 v[88:91], v24, v152, 0
	v_mfma_f32_16x16x4_f32 v[92:95], v24, v156, 0
	v_mfma_f32_16x16x4_f32 v[96:99], v24, v160, 0
	v_mfma_f32_16x16x4_f32 v[84:87], v25, v149, v[84:87]
	v_mfma_f32_16x16x4_f32 v[88:91], v25, v153, v[88:91]
	v_mfma_f32_16x16x4_f32 v[92:95], v25, v157, v[92:95]
	v_mfma_f32_16x16x4_f32 v[96:99], v25, v161, v[96:99]
	v_mfma_f32_16x16x4_f32 v[84:87], v26, v150, v[84:87]
	v_mfma_f32_16x16x4_f32 v[88:91], v26, v154, v[88:91]
	v_mfma_f32_16x16x4_f32 v[92:95], v26, v158, v[92:95]
	v_mfma_f32_16x16x4_f32 v[96:99], v26, v162, v[96:99]
	v_mfma_f32_16x16x4_f32 v[84:87], v27, v151, v[84:87]
	v_mfma_f32_16x16x4_f32 v[88:91], v27, v155, v[88:91]
	v_mfma_f32_16x16x4_f32 v[92:95], v27, v159, v[92:95]
	v_mfma_f32_16x16x4_f32 v[96:99], v27, v163, v[96:99]
	s_nop 7
	s_nop 7
	s_waitcnt lgkmcnt(0)
	s_barrier
	s_cmp_lt_u32 s0, 2
	s_cbranch_scc0 .Lpp_out_w
; DEVI bf16_t f2bf(float a) { return (bf16_t)(pack2(a, 0.f) & 0xffff); }
; DEVI void prep_item(const Params& p, int j, int n, int h, char* smem) {
;     ...
;     bf16_t* dst = r1 + (isu ? 2048 : 1024) + h * 128 + (c & 127);
; #pragma unroll
;     for (int i = 0; i < 64; ++i) {
;       const int t = t0 + i;
;       if (t >= 0) dst[(size_t)t * 3072] = f2bf(x[i]);
;     }
	s_lshl_b32 s1, s0, 7
	v_lshlrev_b32_e32 v14, 1, v12
	v_lshl_add_u32 v14, v13, 10, v14
	v_add3_u32 v14, v14, s1, 32
	v_cvt_pk_bf16_f32 v2, v36, v36
	ds_write_b16 v14, v2 offset:0
	v_cvt_pk_bf16_f32 v3, v37, v37
	ds_write_b16 v14, v3 offset:256
	v_cvt_pk_bf16_f32 v4, v38, v38
	ds_write_b16 v14, v4 offset:512
	v_cvt_pk_bf16_f32 v5, v39, v39
	ds_write_b16 v14, v5 offset:768
	v_cvt_pk_bf16_f32 v2, v52, v52
	ds_write_b16 v14, v2 offset:4096
	v_cvt_pk_bf16_f32 v3, v53, v53
	ds_write_b16 v14, v3 offset:4352
	v_cvt_pk_bf16_f32 v4, v54, v54
	ds_write_b16 v14, v4 offset:4608
	v_cvt_pk_bf16_f32 v5, v55, v55
	ds_write_b16 v14, v5 offset:4864
	v_cvt_pk_bf16_f32 v2, v68, v68
	ds_write_b16 v14, v2 offset:8192
	v_cvt_pk_bf16_f32 v3, v69, v69
	ds_write_b16 v14, v3 offset:8448
	v_cvt_pk_bf16_f32 v4, v70, v70
	ds_write_b16 v14, v4 offset:8704
	v_cvt_pk_bf16_f32 v5, v71, v71
	ds_write_b16 v14, v5 offset:8960
	v_cvt_pk_bf16_f32 v2, v84, v84
	ds_write_b16 v14, v2 offset:12288
	v_cvt_pk_bf16_f32 v3, v85, v85
	ds_write_b16 v14, v3 offset:12544
	v_cvt_pk_bf16_f32 v4, v86, v86
	ds_write_b16 v14, v4 offset:12800
	v_cvt_pk_bf16_f32 v5, v87, v87
	ds_write_b16 v14, v5 offset:13056
	v_cvt_pk_bf16_f32 v2, v40, v40
	ds_write_b16 v14, v2 offset:32
	v_cvt_pk_bf16_f32 v3, v41, v41
	ds_write_b16 v14, v3 offset:288
	v_cvt_pk_bf16_f32 v4, v42, v42
	ds_write_b16 v14, v4 offset:544
	v_cvt_pk_bf16_f32 v5, v43, v43
	ds_write_b16 v14, v5 offset:800
	v_cvt_pk_bf16_f32 v2, v56, v56
	ds_write_b16 v14, v2 offset:4128
	v_cvt_pk_bf16_f32 v3, v57, v57
	ds_write_b16 v14, v3 offset:4384
	v_cvt_pk_bf16_f32 v4, v58, v58
	ds_write_b16 v14, v4 offset:4640
	v_cvt_pk_bf16_f32 v5, v59, v59
	ds_write_b16 v14, v5 offset:4896
	v_cvt_pk_bf16_f32 v2, v72, v72
	ds_write_b16 v14, v2 offset:8224
	v_cvt_pk_bf16_f32 v3, v73, v73
	ds_write_b16 v14, v3 offset:8480
	v_cvt_pk_bf16_f32 v4, v74, v74
	ds_write_b16 v14, v4 offset:8736
	v_cvt_pk_bf16_f32 v5, v75, v75
	ds_write_b16 v14, v5 offset:8992
	v_cvt_pk_bf16_f32 v2, v88, v88
	ds_write_b16 v14, v2 offset:12320
	v_cvt_pk_bf16_f32 v3, v89, v89
	ds_write_b16 v14, v3 offset:12576
	v_cvt_pk_bf16_f32 v4, v90, v90
	ds_write_b16 v14, v4 offset:12832
	v_cvt_pk_bf16_f32 v5, v91, v91
	ds_write_b16 v14, v5 offset:13088
	v_cvt_pk_bf16_f32 v2, v44, v44
	ds_write_b16 v14, v2 offset:64
	v_cvt_pk_bf16_f32 v3, v45, v45
	ds_write_b16 v14, v3 offset:320
	v_cvt_pk_bf16_f32 v4, v46, v46
	ds_write_b16 v14, v4 offset:576
	v_cvt_pk_bf16_f32 v5, v47, v47
	ds_write_b16 v14, v5 offset:832
	v_cvt_pk_bf16_f32 v2, v60, v60
	ds_write_b16 v14, v2 offset:4160
	v_cvt_pk_bf16_f32 v3, v61, v61
	ds_write_b16 v14, v3 offset:4416
	v_cvt_pk_bf16_f32 v4, v62, v62
	ds_write_b16 v14, v4 offset:4672
	v_cvt_pk_bf16_f32 v5, v63, v63
	ds_write_b16 v14, v5 offset:4928
	v_cvt_pk_bf16_f32 v2, v76, v76
	ds_write_b16 v14, v2 offset:8256
	v_cvt_pk_bf16_f32 v3, v77, v77
	ds_write_b16 v14, v3 offset:8512
	v_cvt_pk_bf16_f32 v4, v78, v78
	ds_write_b16 v14, v4 offset:8768
	v_cvt_pk_bf16_f32 v5, v79, v79
	ds_write_b16 v14, v5 offset:9024
	v_cvt_pk_bf16_f32 v2, v92, v92
	ds_write_b16 v14, v2 offset:12352
	v_cvt_pk_bf16_f32 v3, v93, v93
	ds_write_b16 v14, v3 offset:12608
	v_cvt_pk_bf16_f32 v4, v94, v94
	ds_write_b16 v14, v4 offset:12864
	v_cvt_pk_bf16_f32 v5, v95, v95
	ds_write_b16 v14, v5 offset:13120
	v_cvt_pk_bf16_f32 v2, v48, v48
	ds_write_b16 v14, v2 offset:96
	v_cvt_pk_bf16_f32 v3, v49, v49
	ds_write_b16 v14, v3 offset:352
	v_cvt_pk_bf16_f32 v4, v50, v50
	ds_write_b16 v14, v4 offset:608
	v_cvt_pk_bf16_f32 v5, v51, v51
	ds_write_b16 v14, v5 offset:864
	v_cvt_pk_bf16_f32 v2, v64, v64
	ds_write_b16 v14, v2 offset:4192
	v_cvt_pk_bf16_f32 v3, v65, v65
	ds_write_b16 v14, v3 offset:4448
	v_cvt_pk_bf16_f32 v4, v66, v66
	ds_write_b16 v14, v4 offset:4704
	v_cvt_pk_bf16_f32 v5, v67, v67
	ds_write_b16 v14, v5 offset:4960
	v_cvt_pk_bf16_f32 v2, v80, v80
	ds_write_b16 v14, v2 offset:8288
	v_cvt_pk_bf16_f32 v3, v81, v81
	ds_write_b16 v14, v3 offset:8544
	v_cvt_pk_bf16_f32 v4, v82, v82
	ds_write_b16 v14, v4 offset:8800
	v_cvt_pk_bf16_f32 v5, v83, v83
	ds_write_b16 v14, v5 offset:9056
	v_cvt_pk_bf16_f32 v2, v96, v96
	ds_write_b16 v14, v2 offset:12384
	v_cvt_pk_bf16_f32 v3, v97, v97
	ds_write_b16 v14, v3 offset:12640
	v_cvt_pk_bf16_f32 v4, v98, v98
	ds_write_b16 v14, v4 offset:12896
	v_cvt_pk_bf16_f32 v5, v99, v99
	ds_write_b16 v14, v5 offset:13152
	s_branch .Lpp_out_done
; DEVI bf16_t f2bf(float a) { return (bf16_t)(pack2(a, 0.f) & 0xffff); }
; DEVI void prep_item(const Params& p, int j, int n, int h, char* smem) {
;     ...
;     bf16_t* dst = r1 + (isu ? 2048 : 1024) + h * 128 + (c & 127);
; #pragma unroll
;     for (int i = 0; i < 64; ++i) {
;       const int t = t0 + i;
;       if (t >= 0) dst[(size_t)t * 3072] = f2bf(x[i]);
;     }
.Lpp_out_w:
	s_sub_u32 s1, s0, 2
	s_lshl_b32 s1, s1, 6
	v_lshlrev_b32_e32 v15, 2, v13
	v_add_u32_e32 v16, 0, v12
	v_add_u32_e32 v16, s1, v16
	v_and_b32_e32 v17, 0x63, v16
	v_and_b32_e32 v18, 12, v16
	v_lshl_or_b32 v17, v18, 1, v17
	v_and_b32_e32 v18, 16, v16
	v_lshrrev_b32_e32 v18, 2, v18
	v_or_b32_e32 v17, v17, v18
	v_lshrrev_b32_e32 v18, 3, v17
	v_and_b32_e32 v19, 7, v17
	v_lshlrev_b32_e32 v19, 1, v19
	v_lshl_add_u32 v19, v18, 8, v19
	v_add_u32_e32 v19, 17440, v19
	v_or_b32_e32 v20, 0, v15
	v_xor_b32_e32 v20, v20, v18
	v_lshl_add_u32 v20, v20, 4, v19
	v_cvt_pk_bf16_f32 v2, v36, v36
	ds_write_b16 v20, v2 offset:0
	v_cvt_pk_bf16_f32 v3, v52, v52
	ds_write_b16 v20, v3 offset:4096
	v_cvt_pk_bf16_f32 v4, v68, v68
	ds_write_b16 v20, v4 offset:8192
	v_cvt_pk_bf16_f32 v5, v84, v84
	ds_write_b16 v20, v5 offset:12288
	v_or_b32_e32 v21, 1, v15
	v_xor_b32_e32 v21, v21, v18
	v_lshl_add_u32 v21, v21, 4, v19
	v_cvt_pk_bf16_f32 v2, v37, v37
	ds_write_b16 v21, v2 offset:0
	v_cvt_pk_bf16_f32 v3, v53, v53
	ds_write_b16 v21, v3 offset:4096
	v_cvt_pk_bf16_f32 v4, v69, v69
	ds_write_b16 v21, v4 offset:8192
	v_cvt_pk_bf16_f32 v5, v85, v85
	ds_write_b16 v21, v5 offset:12288
	v_or_b32_e32 v22, 2, v15
	v_xor_b32_e32 v22, v22, v18
	v_lshl_add_u32 v22, v22, 4, v19
	v_cvt_pk_bf16_f32 v2, v38, v38
	ds_write_b16 v22, v2 offset:0
	v_cvt_pk_bf16_f32 v3, v54, v54
	ds_write_b16 v22, v3 offset:4096
	v_cvt_pk_bf16_f32 v4, v70, v70
	ds_write_b16 v22, v4 offset:8192
	v_cvt_pk_bf16_f32 v5, v86, v86
	ds_write_b16 v22, v5 offset:12288
	v_or_b32_e32 v23, 3, v15
	v_xor_b32_e32 v23, v23, v18
	v_lshl_add_u32 v23, v23, 4, v19
	v_cvt_pk_bf16_f32 v2, v39, v39
	ds_write_b16 v23, v2 offset:0
	v_cvt_pk_bf16_f32 v3, v55, v55
	ds_write_b16 v23, v3 offset:4096
	v_cvt_pk_bf16_f32 v4, v71, v71
	ds_write_b16 v23, v4 offset:8192
	v_cvt_pk_bf16_f32 v5, v87, v87
	ds_write_b16 v23, v5 offset:12288
	v_add_u32_e32 v16, 16, v12
	v_add_u32_e32 v16, s1, v16
	v_and_b32_e32 v17, 0x63, v16
	v_and_b32_e32 v18, 12, v16
	v_lshl_or_b32 v17, v18, 1, v17
	v_and_b32_e32 v18, 16, v16
	v_lshrrev_b32_e32 v18, 2, v18
	v_or_b32_e32 v17, v17, v18
	v_lshrrev_b32_e32 v18, 3, v17
	v_and_b32_e32 v19, 7, v17
	v_lshlrev_b32_e32 v19, 1, v19
	v_lshl_add_u32 v19, v18, 8, v19
	v_add_u32_e32 v19, 17440, v19
	v_or_b32_e32 v20, 0, v15
	v_xor_b32_e32 v20, v20, v18
	v_lshl_add_u32 v20, v20, 4, v19
	v_cvt_pk_bf16_f32 v2, v40, v40
	ds_write_b16 v20, v2 offset:0
	v_cvt_pk_bf16_f32 v3, v56, v56
	ds_write_b16 v20, v3 offset:4096
	v_cvt_pk_bf16_f32 v4, v72, v72
	ds_write_b16 v20, v4 offset:8192
	v_cvt_pk_bf16_f32 v5, v88, v88
	ds_write_b16 v20, v5 offset:12288
	v_or_b32_e32 v21, 1, v15
	v_xor_b32_e32 v21, v21, v18
	v_lshl_add_u32 v21, v21, 4, v19
	v_cvt_pk_bf16_f32 v2, v41, v41
	ds_write_b16 v21, v2 offset:0
	v_cvt_pk_bf16_f32 v3, v57, v57
	ds_write_b16 v21, v3 offset:4096
	v_cvt_pk_bf16_f32 v4, v73, v73
	ds_write_b16 v21, v4 offset:8192
	v_cvt_pk_bf16_f32 v5, v89, v89
	ds_write_b16 v21, v5 offset:12288
	v_or_b32_e32 v22, 2, v15
	v_xor_b32_e32 v22, v22, v18
	v_lshl_add_u32 v22, v22, 4, v19
	v_cvt_pk_bf16_f32 v2, v42, v42
	ds_write_b16 v22, v2 offset:0
	v_cvt_pk_bf16_f32 v3, v58, v58
	ds_write_b16 v22, v3 offset:4096
	v_cvt_pk_bf16_f32 v4, v74, v74
	ds_write_b16 v22, v4 offset:8192
	v_cvt_pk_bf16_f32 v5, v90, v90
	ds_write_b16 v22, v5 offset:12288
	v_or_b32_e32 v23, 3, v15
	v_xor_b32_e32 v23, v23, v18
	v_lshl_add_u32 v23, v23, 4, v19
	v_cvt_pk_bf16_f32 v2, v43, v43
	ds_write_b16 v23, v2 offset:0
	v_cvt_pk_bf16_f32 v3, v59, v59
	ds_write_b16 v23, v3 offset:4096
	v_cvt_pk_bf16_f32 v4, v75, v75
	ds_write_b16 v23, v4 offset:8192
	v_cvt_pk_bf16_f32 v5, v91, v91
	ds_write_b16 v23, v5 offset:12288
	v_add_u32_e32 v16, 32, v12
	v_add_u32_e32 v16, s1, v16
	v_and_b32_e32 v17, 0x63, v16
	v_and_b32_e32 v18, 12, v16
	v_lshl_or_b32 v17, v18, 1, v17
	v_and_b32_e32 v18, 16, v16
	v_lshrrev_b32_e32 v18, 2, v18
	v_or_b32_e32 v17, v17, v18
	v_lshrrev_b32_e32 v18, 3, v17
	v_and_b32_e32 v19, 7, v17
	v_lshlrev_b32_e32 v19, 1, v19
	v_lshl_add_u32 v19, v18, 8, v19
	v_add_u32_e32 v19, 17440, v19
	v_or_b32_e32 v20, 0, v15
	v_xor_b32_e32 v20, v20, v18
	v_lshl_add_u32 v20, v20, 4, v19
	v_cvt_pk_bf16_f32 v2, v44, v44
	ds_write_b16 v20, v2 offset:0
	v_cvt_pk_bf16_f32 v3, v60, v60
	ds_write_b16 v20, v3 offset:4096
	v_cvt_pk_bf16_f32 v4, v76, v76
	ds_write_b16 v20, v4 offset:8192
	v_cvt_pk_bf16_f32 v5, v92, v92
	ds_write_b16 v20, v5 offset:12288
	v_or_b32_e32 v21, 1, v15
	v_xor_b32_e32 v21, v21, v18
	v_lshl_add_u32 v21, v21, 4, v19
	v_cvt_pk_bf16_f32 v2, v45, v45
; DEVI bf16_t f2bf(float a) { return (bf16_t)(pack2(a, 0.f) & 0xffff); }
; DEVI void prep_item(const Params& p, int j, int n, int h, char* smem) {
;     ...
;     bf16_t* dst = r1 + (isu ? 2048 : 1024) + h * 128 + (c & 127);
; #pragma unroll
;     for (int i = 0; i < 64; ++i) {
;       const int t = t0 + i;
;       if (t >= 0) dst[(size_t)t * 3072] = f2bf(x[i]);
;     }
	ds_write_b16 v21, v2 offset:0
	v_cvt_pk_bf16_f32 v3, v61, v61
	ds_write_b16 v21, v3 offset:4096
	v_cvt_pk_bf16_f32 v4, v77, v77
	ds_write_b16 v21, v4 offset:8192
	v_cvt_pk_bf16_f32 v5, v93, v93
	ds_write_b16 v21, v5 offset:12288
	v_or_b32_e32 v22, 2, v15
	v_xor_b32_e32 v22, v22, v18
	v_lshl_add_u32 v22, v22, 4, v19
	v_cvt_pk_bf16_f32 v2, v46, v46
	ds_write_b16 v22, v2 offset:0
	v_cvt_pk_bf16_f32 v3, v62, v62
	ds_write_b16 v22, v3 offset:4096
	v_cvt_pk_bf16_f32 v4, v78, v78
	ds_write_b16 v22, v4 offset:8192
	v_cvt_pk_bf16_f32 v5, v94, v94
	ds_write_b16 v22, v5 offset:12288
	v_or_b32_e32 v23, 3, v15
	v_xor_b32_e32 v23, v23, v18
	v_lshl_add_u32 v23, v23, 4, v19
	v_cvt_pk_bf16_f32 v2, v47, v47
	ds_write_b16 v23, v2 offset:0
	v_cvt_pk_bf16_f32 v3, v63, v63
	ds_write_b16 v23, v3 offset:4096
	v_cvt_pk_bf16_f32 v4, v79, v79
	ds_write_b16 v23, v4 offset:8192
	v_cvt_pk_bf16_f32 v5, v95, v95
	ds_write_b16 v23, v5 offset:12288
	v_add_u32_e32 v16, 48, v12
	v_add_u32_e32 v16, s1, v16
	v_and_b32_e32 v17, 0x63, v16
	v_and_b32_e32 v18, 12, v16
	v_lshl_or_b32 v17, v18, 1, v17
	v_and_b32_e32 v18, 16, v16
	v_lshrrev_b32_e32 v18, 2, v18
	v_or_b32_e32 v17, v17, v18
	v_lshrrev_b32_e32 v18, 3, v17
	v_and_b32_e32 v19, 7, v17
	v_lshlrev_b32_e32 v19, 1, v19
	v_lshl_add_u32 v19, v18, 8, v19
	v_add_u32_e32 v19, 17440, v19
	v_or_b32_e32 v20, 0, v15
	v_xor_b32_e32 v20, v20, v18
	v_lshl_add_u32 v20, v20, 4, v19
	v_cvt_pk_bf16_f32 v2, v48, v48
	ds_write_b16 v20, v2 offset:0
	v_cvt_pk_bf16_f32 v3, v64, v64
	ds_write_b16 v20, v3 offset:4096
	v_cvt_pk_bf16_f32 v4, v80, v80
	ds_write_b16 v20, v4 offset:8192
	v_cvt_pk_bf16_f32 v5, v96, v96
	ds_write_b16 v20, v5 offset:12288
	v_or_b32_e32 v21, 1, v15
	v_xor_b32_e32 v21, v21, v18
	v_lshl_add_u32 v21, v21, 4, v19
	v_cvt_pk_bf16_f32 v2, v49, v49
	ds_write_b16 v21, v2 offset:0
	v_cvt_pk_bf16_f32 v3, v65, v65
	ds_write_b16 v21, v3 offset:4096
	v_cvt_pk_bf16_f32 v4, v81, v81
	ds_write_b16 v21, v4 offset:8192
	v_cvt_pk_bf16_f32 v5, v97, v97
	ds_write_b16 v21, v5 offset:12288
	v_or_b32_e32 v22, 2, v15
	v_xor_b32_e32 v22, v22, v18
	v_lshl_add_u32 v22, v22, 4, v19
	v_cvt_pk_bf16_f32 v2, v50, v50
	ds_write_b16 v22, v2 offset:0
	v_cvt_pk_bf16_f32 v3, v66, v66
	ds_write_b16 v22, v3 offset:4096
	v_cvt_pk_bf16_f32 v4, v82, v82
	ds_write_b16 v22, v4 offset:8192
	v_cvt_pk_bf16_f32 v5, v98, v98
	ds_write_b16 v22, v5 offset:12288
	v_or_b32_e32 v23, 3, v15
	v_xor_b32_e32 v23, v23, v18
	v_lshl_add_u32 v23, v23, 4, v19
	v_cvt_pk_bf16_f32 v2, v51, v51
	ds_write_b16 v23, v2 offset:0
	v_cvt_pk_bf16_f32 v3, v67, v67
	ds_write_b16 v23, v3 offset:4096
	v_cvt_pk_bf16_f32 v4, v83, v83
	ds_write_b16 v23, v4 offset:8192
	v_cvt_pk_bf16_f32 v5, v99, v99
	ds_write_b16 v23, v5 offset:12288
.Lpp_out_done:
	s_waitcnt lgkmcnt(0)
	s_barrier
	v_readlane_b32 s0, v247, 26
	v_readlane_b32 s1, v247, 27
	v_lshlrev_b32_e32 v85, 4, v34
	ds_read_b128 v[4:7], v85 offset:32
	ds_read_b128 v[8:11], v85 offset:4128
	ds_read_b128 v[12:15], v85 offset:8224
	ds_read_b128 v[16:19], v85 offset:12320
	ds_read_b128 v[20:23], v85 offset:17440
	ds_read_b128 v[24:27], v85 offset:21536
	ds_read_b128 v[28:31], v85 offset:25632
	ds_read_b128 v[36:39], v85 offset:29728
	v_lshrrev_b32_e32 v86, 4, v34
	v_and_b32_e32 v87, 15, v34
	v_and_b32_e32 v70, 15, v86
	v_xor_b32_e32 v70, v70, v87
	v_add_u32_e32 v86, s43, v86
	v_mad_u64_u32 v[72:73], s[16:17], v86, v222, 0
	v_lshl_add_u64 v[72:73], s[0:1], 0, v[72:73]
	v_lshl_add_u64 v[72:73], v[72:73], 0, s[62:63]
	v_lshlrev_b32_e32 v0, 4, v87
	v_add_u32_e32 v0, 0x1000, v0
	v_lshl_add_u64 v[74:75], v[72:73], 0, v[0:1]
	v_lshlrev_b32_e32 v0, 4, v70
	v_add_u32_e32 v0, 0x800, v0
	v_lshl_add_u64 v[72:73], v[72:73], 0, v[0:1]
	s_mov_b32 s16, 0xfffe8000
	s_mov_b32 s17, -1
	s_waitcnt lgkmcnt(0)
	global_store_dwordx4 v[74:75], v[16:19], off
	global_store_dwordx4 v[72:73], v[36:39], off
	s_cmp_lt_i32 s44, 1
	s_cbranch_scc1 .LBB0_1295
	v_lshl_add_u64 v[74:75], v[74:75], 0, s[16:17]
	v_lshl_add_u64 v[72:73], v[72:73], 0, s[16:17]
	global_store_dwordx4 v[74:75], v[12:15], off
	global_store_dwordx4 v[72:73], v[28:31], off
	v_lshl_add_u64 v[74:75], v[74:75], 0, s[16:17]
	v_lshl_add_u64 v[72:73], v[72:73], 0, s[16:17]
	global_store_dwordx4 v[74:75], v[8:11], off
	global_store_dwordx4 v[72:73], v[24:27], off
	v_lshl_add_u64 v[74:75], v[74:75], 0, s[16:17]
	v_lshl_add_u64 v[72:73], v[72:73], 0, s[16:17]
	global_store_dwordx4 v[74:75], v[4:7], off
	global_store_dwordx4 v[72:73], v[20:23], off
.LBB0_1295:
	s_branch .LBB0_1242
.LBB0_1297:
	s_mov_b64 s[6:7], 0
	s_mov_b64 s[0:1], -1
